# removed cooperative-groups grid.sync at kernel start (XCD barrier census is self-contained)
# baseline (speedup 1.0000x reference)
.LBB0_7:
	s_or_b64 exec, exec, s[4:5]
	s_load_dwordx16 s[52:67], s[0:1], 0x0
	s_load_dwordx16 s[68:83], s[0:1], 0x40
	s_add_u32 s0, s90, 0x2180000
	s_addc_u32 s1, s91, 0
	v_writelane_b32 v255, s0, 2
	v_mov_b32_e32 v10, v208
	v_writelane_b32 v255, s1, 3
	s_waitcnt lgkmcnt(0)
	s_cmpk_gt_i32 s20, 0xbf
	v_ashrrev_i32_e32 v11, 31, v10
	v_and_b32_e32 v32, 31, v10
	s_cbranch_scc1 .LBB0_28
	s_movk_i32 s0, 0x4400
	v_lshlrev_b32_e32 v0, 2, v32
	v_cmp_gt_i32_e32 vcc, s0, v10
	v_ashrrev_i32_e32 v14, 5, v10
	v_or_b32_e32 v2, 0x11000, v0
	s_movk_i32 s0, 0x880
	v_mad_u64_u32 v[4:5], s[0:1], v14, s0, v[2:3]
	s_movk_i32 s0, 0x220
	s_nop 0
	v_cmp_gt_i32_e64 s[4:5], s0, v10
	v_readlane_b32 s0, v255, 2
	v_lshlrev_b32_e32 v12, 6, v14
	v_mov_b32_e32 v1, 0
	v_readlane_b32 s1, v255, 3
	s_movk_i32 s12, 0x3000
	v_mov_b32_e32 v8, s54
	v_lshl_add_u64 v[6:7], s[0:1], 0, v[0:1]
	v_mad_i64_i32 v[12:13], s[0:1], v12, s12, 0
	v_or_b32_e32 v12, v12, v0
	v_mov_b32_e32 v9, s55
	v_lshl_add_u64 v[12:13], s[60:61], 0, v[12:13]
	s_mov_b64 s[0:1], 0x9000
	v_lshlrev_b32_e32 v3, 2, v10
	v_lshl_add_u64 v[8:9], v[10:11], 2, v[8:9]
	v_lshl_add_u64 v[12:13], v[12:13], 0, s[0:1]
	v_lshlrev_b32_e32 v5, 8, v14
	s_movk_i32 s13, 0x4000
	s_mov_b64 s[2:3], 0x800
	s_movk_i32 s14, 0x41ff
	s_mov_b32 s15, 0xffff7000
	s_movk_i32 s16, 0xa000
	s_movk_i32 s17, 0xd000
	s_mov_b64 s[6:7], 0xc000
	v_add_u32_e32 v33, 0x400, v4
	s_mov_b32 s18, s20
	s_branch .LBB0_20
